# 7.11 back-edge rotation: GEMM K-loop counter/pointer-advance and next-iteration pointer-select SALU moved in front of the loop-back barrier (head starts with LDS reads)
# baseline (speedup 1.0000x reference)
.Lgprio0:
	v_add_u32_e32 v236, 0x10000, v175
	v_add_u32_e32 v237, 0x14000, v175
	v_add_u32_e32 v238, 0x18000, v175
	v_add_u32_e32 v239, 0x1c000, v175
	s_add_u32 s42, s40, 0xfff80080
	s_addc_u32 s43, s41, -1
	s_add_i32 s52, 0, 0x10000
	s_cmp_eq_u32 s51, 28
	s_cselect_b32 s45, s13, s43
	s_cselect_b32 s44, s47, s42
	s_cselect_b32 s43, s11, s50
	s_cselect_b32 s42, s48, s49
	s_add_i32 s54, 0, 0x14000
.LBB0_169:
	ds_read_b128 v[130:133], v236
	ds_read_b128 v[134:137], v236 offset:1024
	ds_read_b128 v[138:141], v236 offset:2048
	ds_read_b128 v[142:145], v236 offset:3072
	ds_read_b128 v[170:173], v237
	ds_read_b128 v[184:187], v237 offset:1024
	ds_read_b128 v[188:191], v237 offset:2048
	ds_read_b128 v[192:195], v237 offset:3072
	s_add_i32 m0, s14, 0xc000
	ds_read_b128 v[196:199], v183
	ds_read_b128 v[200:203], v183 offset:1024
	ds_read_b128 v[210:213], v183 offset:2048
	ds_read_b128 v[214:217], v183 offset:3072
	ds_read_b128 v[218:221], v183 offset:4096
	ds_read_b128 v[222:225], v183 offset:5120
	ds_read_b128 v[226:229], v183 offset:6144
	ds_read_b128 v[230:233], v183 offset:7168
	global_load_lds_dwordx4 v166, s[40:41]
	s_add_i32 m0, s14, 0xe000
	s_nop 0
	global_load_lds_dwordx4 v168, s[40:41]
	s_waitcnt vmcnt(8) lgkmcnt(0)
	s_barrier
	v_mfma_f32_16x16x32_bf16 v[126:129], v[130:133], v[196:199], v[126:129]
	v_mfma_f32_16x16x32_bf16 v[122:125], v[138:141], v[196:199], v[122:125]
	v_mfma_f32_16x16x32_bf16 v[118:121], v[130:133], v[210:213], v[118:121]
	v_mfma_f32_16x16x32_bf16 v[110:113], v[138:141], v[210:213], v[110:113]
	v_mfma_f32_16x16x32_bf16 v[102:105], v[130:133], v[218:221], v[102:105]
	v_mfma_f32_16x16x32_bf16 v[94:97], v[138:141], v[218:221], v[94:97]
	v_mfma_f32_16x16x32_bf16 v[86:89], v[130:133], v[226:229], v[86:89]
	v_mfma_f32_16x16x32_bf16 v[78:81], v[138:141], v[226:229], v[78:81]
	v_mfma_f32_16x16x32_bf16 v[126:129], v[134:137], v[200:203], v[126:129]
	v_mfma_f32_16x16x32_bf16 v[122:125], v[142:145], v[200:203], v[122:125]
	v_mfma_f32_16x16x32_bf16 v[118:121], v[134:137], v[214:217], v[118:121]
	v_mfma_f32_16x16x32_bf16 v[110:113], v[142:145], v[214:217], v[110:113]
	v_mfma_f32_16x16x32_bf16 v[102:105], v[134:137], v[222:225], v[102:105]
	v_mfma_f32_16x16x32_bf16 v[94:97], v[142:145], v[222:225], v[94:97]
	v_mfma_f32_16x16x32_bf16 v[86:89], v[134:137], v[230:233], v[86:89]
	v_mfma_f32_16x16x32_bf16 v[78:81], v[142:145], v[230:233], v[78:81]
	v_mfma_f32_16x16x32_bf16 v[114:117], v[170:173], v[196:199], v[114:117]
	v_mfma_f32_16x16x32_bf16 v[106:109], v[188:191], v[196:199], v[106:109]
	v_mfma_f32_16x16x32_bf16 v[98:101], v[170:173], v[210:213], v[98:101]
	v_mfma_f32_16x16x32_bf16 v[90:93], v[188:191], v[210:213], v[90:93]
	v_mfma_f32_16x16x32_bf16 v[82:85], v[170:173], v[218:221], v[82:85]
	v_mfma_f32_16x16x32_bf16 v[74:77], v[188:191], v[218:221], v[74:77]
	v_mfma_f32_16x16x32_bf16 v[70:73], v[170:173], v[226:229], v[70:73]
	v_mfma_f32_16x16x32_bf16 v[66:69], v[188:191], v[226:229], v[66:69]
	v_mfma_f32_16x16x32_bf16 v[114:117], v[184:187], v[200:203], v[114:117]
	v_mfma_f32_16x16x32_bf16 v[106:109], v[192:195], v[200:203], v[106:109]
	v_mfma_f32_16x16x32_bf16 v[98:101], v[184:187], v[214:217], v[98:101]
	v_mfma_f32_16x16x32_bf16 v[90:93], v[192:195], v[214:217], v[90:93]
	v_mfma_f32_16x16x32_bf16 v[82:85], v[184:187], v[222:225], v[82:85]
	v_mfma_f32_16x16x32_bf16 v[74:77], v[192:195], v[222:225], v[74:77]
	v_mfma_f32_16x16x32_bf16 v[70:73], v[184:187], v[230:233], v[70:73]
	v_mfma_f32_16x16x32_bf16 v[66:69], v[192:195], v[230:233], v[66:69]
	s_barrier
	s_add_i32 s52, s52, s5
	s_mov_b32 m0, s52
	ds_read_b128 v[196:199], v183 offset:16384
	ds_read_b128 v[200:203], v183 offset:17408
	ds_read_b128 v[210:213], v183 offset:18432
	ds_read_b128 v[214:217], v183 offset:19456
	ds_read_b128 v[218:221], v183 offset:20480
	ds_read_b128 v[222:225], v183 offset:21504
	ds_read_b128 v[226:229], v183 offset:22528
	ds_read_b128 v[230:233], v183 offset:23552
	global_load_lds_dwordx4 v162, s[42:43]
	s_add_i32 m0, s52, 0x2000
	s_add_u32 s52, s42, 0x80000
	s_addc_u32 s53, s43, 0
	s_add_i32 s54, s54, s5
	global_load_lds_dwordx4 v158, s[42:43]
	s_mov_b32 m0, s54
	s_nop 0
	global_load_lds_dwordx4 v162, s[52:53]
	s_add_i32 m0, s54, 0x2000
	s_nop 0
	global_load_lds_dwordx4 v158, s[52:53]
	s_mov_b32 m0, s14
	s_nop 0
	global_load_lds_dwordx4 v164, s[44:45]
	s_mov_b32 m0, s15
	s_nop 0
	global_load_lds_dwordx4 v160, s[44:45]
	s_add_u32 s98, s42, 0x80
	s_addc_u32 s99, s43, 0
	s_add_u32 s100, s44, 0x80
	s_addc_u32 s101, s45, 0
	s_waitcnt vmcnt(8) lgkmcnt(0)
	s_barrier
	v_mfma_f32_16x16x32_bf16 v[62:65], v[130:133], v[196:199], v[62:65]
	v_mfma_f32_16x16x32_bf16 v[58:61], v[138:141], v[196:199], v[58:61]
	v_mfma_f32_16x16x32_bf16 v[54:57], v[130:133], v[210:213], v[54:57]
	v_mfma_f32_16x16x32_bf16 v[46:49], v[138:141], v[210:213], v[46:49]
	v_mfma_f32_16x16x32_bf16 v[38:41], v[130:133], v[218:221], v[38:41]
	v_mfma_f32_16x16x32_bf16 v[30:33], v[138:141], v[218:221], v[30:33]
	v_mfma_f32_16x16x32_bf16 v[22:25], v[130:133], v[226:229], v[22:25]
	v_mfma_f32_16x16x32_bf16 v[14:17], v[138:141], v[226:229], v[14:17]
	v_mfma_f32_16x16x32_bf16 v[62:65], v[134:137], v[200:203], v[62:65]
	v_mfma_f32_16x16x32_bf16 v[58:61], v[142:145], v[200:203], v[58:61]
	v_mfma_f32_16x16x32_bf16 v[54:57], v[134:137], v[214:217], v[54:57]
	v_mfma_f32_16x16x32_bf16 v[46:49], v[142:145], v[214:217], v[46:49]
	v_mfma_f32_16x16x32_bf16 v[38:41], v[134:137], v[222:225], v[38:41]
	v_mfma_f32_16x16x32_bf16 v[30:33], v[142:145], v[222:225], v[30:33]
	v_mfma_f32_16x16x32_bf16 v[22:25], v[134:137], v[230:233], v[22:25]
	v_mfma_f32_16x16x32_bf16 v[14:17], v[142:145], v[230:233], v[14:17]
	v_mfma_f32_16x16x32_bf16 v[50:53], v[170:173], v[196:199], v[50:53]
	v_mfma_f32_16x16x32_bf16 v[42:45], v[188:191], v[196:199], v[42:45]
	v_mfma_f32_16x16x32_bf16 v[34:37], v[170:173], v[210:213], v[34:37]
	v_mfma_f32_16x16x32_bf16 v[26:29], v[188:191], v[210:213], v[26:29]
	v_mfma_f32_16x16x32_bf16 v[18:21], v[170:173], v[218:221], v[18:21]
	v_mfma_f32_16x16x32_bf16 v[10:13], v[188:191], v[218:221], v[10:13]
	v_mfma_f32_16x16x32_bf16 v[6:9], v[170:173], v[226:229], v[6:9]
	v_mfma_f32_16x16x32_bf16 v[2:5], v[188:191], v[226:229], v[2:5]
	v_mfma_f32_16x16x32_bf16 v[50:53], v[184:187], v[200:203], v[50:53]
	v_mfma_f32_16x16x32_bf16 v[42:45], v[192:195], v[200:203], v[42:45]
	v_mfma_f32_16x16x32_bf16 v[34:37], v[184:187], v[214:217], v[34:37]
	v_mfma_f32_16x16x32_bf16 v[26:29], v[192:195], v[214:217], v[26:29]
	v_mfma_f32_16x16x32_bf16 v[18:21], v[184:187], v[222:225], v[18:21]
	v_mfma_f32_16x16x32_bf16 v[10:13], v[192:195], v[222:225], v[10:13]
	v_mfma_f32_16x16x32_bf16 v[6:9], v[184:187], v[230:233], v[6:9]
	v_mfma_f32_16x16x32_bf16 v[2:5], v[192:195], v[230:233], v[2:5]
	s_barrier
	s_add_i32 s52, 0, 0x18000
	s_add_i32 s53, 0, 0x1c000
	ds_read_b128 v[130:133], v238
	ds_read_b128 v[134:137], v238 offset:1024
	ds_read_b128 v[138:141], v238 offset:2048
	ds_read_b128 v[142:145], v238 offset:3072
	ds_read_b128 v[170:173], v239
	ds_read_b128 v[184:187], v239 offset:1024
	ds_read_b128 v[188:191], v239 offset:2048
	ds_read_b128 v[192:195], v239 offset:3072
	s_add_u32 s44, s44, 0x80000
	s_addc_u32 s45, s45, 0
	s_mov_b32 m0, s16
	ds_read_b128 v[196:199], v183 offset:32768
	ds_read_b128 v[200:203], v183 offset:33792
	ds_read_b128 v[210:213], v183 offset:34816
	ds_read_b128 v[214:217], v183 offset:35840
	ds_read_b128 v[218:221], v183 offset:36864
	ds_read_b128 v[222:225], v183 offset:37888
	ds_read_b128 v[226:229], v183 offset:38912
	ds_read_b128 v[230:233], v183 offset:39936
	global_load_lds_dwordx4 v164, s[44:45]
	s_mov_b32 m0, s18
	s_nop 0
	global_load_lds_dwordx4 v160, s[44:45]
	s_waitcnt vmcnt(8) lgkmcnt(0)
	s_barrier
	v_mfma_f32_16x16x32_bf16 v[126:129], v[130:133], v[196:199], v[126:129]
	v_mfma_f32_16x16x32_bf16 v[122:125], v[138:141], v[196:199], v[122:125]
	v_mfma_f32_16x16x32_bf16 v[118:121], v[130:133], v[210:213], v[118:121]
	v_mfma_f32_16x16x32_bf16 v[110:113], v[138:141], v[210:213], v[110:113]
	v_mfma_f32_16x16x32_bf16 v[102:105], v[130:133], v[218:221], v[102:105]
	v_mfma_f32_16x16x32_bf16 v[94:97], v[138:141], v[218:221], v[94:97]
	v_mfma_f32_16x16x32_bf16 v[86:89], v[130:133], v[226:229], v[86:89]
	v_mfma_f32_16x16x32_bf16 v[78:81], v[138:141], v[226:229], v[78:81]
	v_mfma_f32_16x16x32_bf16 v[126:129], v[134:137], v[200:203], v[126:129]
	v_mfma_f32_16x16x32_bf16 v[122:125], v[142:145], v[200:203], v[122:125]
	v_mfma_f32_16x16x32_bf16 v[118:121], v[134:137], v[214:217], v[118:121]
	v_mfma_f32_16x16x32_bf16 v[110:113], v[142:145], v[214:217], v[110:113]
	v_mfma_f32_16x16x32_bf16 v[102:105], v[134:137], v[222:225], v[102:105]
	v_mfma_f32_16x16x32_bf16 v[94:97], v[142:145], v[222:225], v[94:97]
	v_mfma_f32_16x16x32_bf16 v[86:89], v[134:137], v[230:233], v[86:89]
	v_mfma_f32_16x16x32_bf16 v[78:81], v[142:145], v[230:233], v[78:81]
	v_mfma_f32_16x16x32_bf16 v[114:117], v[170:173], v[196:199], v[114:117]
	v_mfma_f32_16x16x32_bf16 v[106:109], v[188:191], v[196:199], v[106:109]
	v_mfma_f32_16x16x32_bf16 v[98:101], v[170:173], v[210:213], v[98:101]
	v_mfma_f32_16x16x32_bf16 v[90:93], v[188:191], v[210:213], v[90:93]
	v_mfma_f32_16x16x32_bf16 v[82:85], v[170:173], v[218:221], v[82:85]
	v_mfma_f32_16x16x32_bf16 v[74:77], v[188:191], v[218:221], v[74:77]
	v_mfma_f32_16x16x32_bf16 v[70:73], v[170:173], v[226:229], v[70:73]
	v_mfma_f32_16x16x32_bf16 v[66:69], v[188:191], v[226:229], v[66:69]
	v_mfma_f32_16x16x32_bf16 v[114:117], v[184:187], v[200:203], v[114:117]
	v_mfma_f32_16x16x32_bf16 v[106:109], v[192:195], v[200:203], v[106:109]
	v_mfma_f32_16x16x32_bf16 v[98:101], v[184:187], v[214:217], v[98:101]
	v_mfma_f32_16x16x32_bf16 v[90:93], v[192:195], v[214:217], v[90:93]
	v_mfma_f32_16x16x32_bf16 v[82:85], v[184:187], v[222:225], v[82:85]
	v_mfma_f32_16x16x32_bf16 v[74:77], v[192:195], v[222:225], v[74:77]
	v_mfma_f32_16x16x32_bf16 v[70:73], v[184:187], v[230:233], v[70:73]
	v_mfma_f32_16x16x32_bf16 v[66:69], v[192:195], v[230:233], v[66:69]
	s_barrier
	s_add_i32 s44, s52, s5
	s_mov_b32 m0, s44
	ds_read_b128 v[196:199], v183 offset:49152
	ds_read_b128 v[200:203], v183 offset:50176
	ds_read_b128 v[210:213], v183 offset:51200
	ds_read_b128 v[214:217], v183 offset:52224
	ds_read_b128 v[218:221], v183 offset:53248
	ds_read_b128 v[222:225], v183 offset:54272
	ds_read_b128 v[226:229], v183 offset:55296
	ds_read_b128 v[230:233], v183 offset:56320
	global_load_lds_dwordx4 v162, s[98:99]
	s_add_i32 m0, s44, 0x2000
	s_add_u32 s42, s42, 0x80080
	s_addc_u32 s43, s43, 0
	s_add_i32 s44, s53, s5
	global_load_lds_dwordx4 v158, s[98:99]
	s_mov_b32 m0, s44
	s_nop 0
	global_load_lds_dwordx4 v162, s[42:43]
	s_add_i32 m0, s44, 0x2000
	s_nop 0
	global_load_lds_dwordx4 v158, s[42:43]
	s_mov_b32 m0, s19
	s_nop 0
	global_load_lds_dwordx4 v164, s[100:101]
	s_mov_b32 m0, s25
	s_nop 0
	global_load_lds_dwordx4 v160, s[100:101]
	s_waitcnt vmcnt(8) lgkmcnt(0)
	s_barrier
	v_mfma_f32_16x16x32_bf16 v[62:65], v[130:133], v[196:199], v[62:65]
	v_mfma_f32_16x16x32_bf16 v[58:61], v[138:141], v[196:199], v[58:61]
	v_mfma_f32_16x16x32_bf16 v[54:57], v[130:133], v[210:213], v[54:57]
	v_mfma_f32_16x16x32_bf16 v[46:49], v[138:141], v[210:213], v[46:49]
	v_mfma_f32_16x16x32_bf16 v[38:41], v[130:133], v[218:221], v[38:41]
	v_mfma_f32_16x16x32_bf16 v[30:33], v[138:141], v[218:221], v[30:33]
	v_mfma_f32_16x16x32_bf16 v[22:25], v[130:133], v[226:229], v[22:25]
	v_mfma_f32_16x16x32_bf16 v[14:17], v[138:141], v[226:229], v[14:17]
	v_mfma_f32_16x16x32_bf16 v[62:65], v[134:137], v[200:203], v[62:65]
	v_mfma_f32_16x16x32_bf16 v[58:61], v[142:145], v[200:203], v[58:61]
	v_mfma_f32_16x16x32_bf16 v[54:57], v[134:137], v[214:217], v[54:57]
	v_mfma_f32_16x16x32_bf16 v[46:49], v[142:145], v[214:217], v[46:49]
	v_mfma_f32_16x16x32_bf16 v[38:41], v[134:137], v[222:225], v[38:41]
	v_mfma_f32_16x16x32_bf16 v[30:33], v[142:145], v[222:225], v[30:33]
	v_mfma_f32_16x16x32_bf16 v[22:25], v[134:137], v[230:233], v[22:25]
	v_mfma_f32_16x16x32_bf16 v[14:17], v[142:145], v[230:233], v[14:17]
	v_mfma_f32_16x16x32_bf16 v[50:53], v[170:173], v[196:199], v[50:53]
	v_mfma_f32_16x16x32_bf16 v[42:45], v[188:191], v[196:199], v[42:45]
	v_mfma_f32_16x16x32_bf16 v[34:37], v[170:173], v[210:213], v[34:37]
	v_mfma_f32_16x16x32_bf16 v[26:29], v[188:191], v[210:213], v[26:29]
	v_mfma_f32_16x16x32_bf16 v[18:21], v[170:173], v[218:221], v[18:21]
	v_mfma_f32_16x16x32_bf16 v[10:13], v[188:191], v[218:221], v[10:13]
	v_mfma_f32_16x16x32_bf16 v[6:9], v[170:173], v[226:229], v[6:9]
	v_mfma_f32_16x16x32_bf16 v[2:5], v[188:191], v[226:229], v[2:5]
	v_mfma_f32_16x16x32_bf16 v[50:53], v[184:187], v[200:203], v[50:53]
	v_mfma_f32_16x16x32_bf16 v[42:45], v[192:195], v[200:203], v[42:45]
	v_mfma_f32_16x16x32_bf16 v[34:37], v[184:187], v[214:217], v[34:37]
	v_mfma_f32_16x16x32_bf16 v[26:29], v[192:195], v[214:217], v[26:29]
	v_mfma_f32_16x16x32_bf16 v[18:21], v[184:187], v[222:225], v[18:21]
	v_mfma_f32_16x16x32_bf16 v[10:13], v[192:195], v[222:225], v[10:13]
	v_mfma_f32_16x16x32_bf16 v[6:9], v[184:187], v[230:233], v[6:9]
	v_mfma_f32_16x16x32_bf16 v[2:5], v[192:195], v[230:233], v[2:5]
	s_add_i32 s51, s51, 2
	s_add_u32 s40, s40, 0x100
	s_addc_u32 s41, s41, 0
	s_add_u32 s49, s49, 0x100
	s_addc_u32 s50, s50, 0
	s_add_u32 s42, s40, 0xfff80080
	s_addc_u32 s43, s41, -1
	s_add_i32 s52, 0, 0x10000
	s_cmp_eq_u32 s51, 28
	s_cselect_b32 s45, s13, s43
	s_cselect_b32 s44, s47, s42
	s_cselect_b32 s43, s11, s50
	s_cselect_b32 s42, s48, s49
	s_add_i32 s54, 0, 0x14000
	s_cmp_gt_u32 s51, 29
	s_barrier
	s_cbranch_scc0 .LBB0_169
	s_setprio 0
	s_and_b64 vcc, exec, s[8:9]
	s_cbranch_vccz .LBB0_172
	s_barrier

.Lgprio1:
	v_add_u32_e32 v236, 0x10000, v172
	v_add_u32_e32 v237, 0x14000, v172
	v_add_u32_e32 v238, 0x18000, v172
	v_add_u32_e32 v239, 0x1c000, v172
	s_add_u32 s46, s44, 0xfff80080
	s_addc_u32 s47, s45, -1
	s_add_i32 s58, 0, 0x10000
	s_cmp_eq_u32 s57, 28
	s_cselect_b32 s49, s21, s47
	s_cselect_b32 s48, s50, s46
	s_cselect_b32 s47, s13, s56
	s_cselect_b32 s46, s51, s55
	s_add_i32 s60, 0, 0x14000
.LBB0_516:
	ds_read_b128 v[82:85], v236
	ds_read_b128 v[86:89], v236 offset:1024
	ds_read_b128 v[98:101], v236 offset:2048
	ds_read_b128 v[102:105], v236 offset:3072
	ds_read_b128 v[154:157], v237
	ds_read_b128 v[168:171], v237 offset:1024
	ds_read_b128 v[176:179], v237 offset:2048
	ds_read_b128 v[180:183], v237 offset:3072
	s_add_i32 m0, s14, 0xc000
	ds_read_b128 v[184:187], v174
	ds_read_b128 v[188:191], v174 offset:1024
	ds_read_b128 v[192:195], v174 offset:2048
	ds_read_b128 v[196:199], v174 offset:3072
	ds_read_b128 v[200:203], v174 offset:4096
	ds_read_b128 v[210:213], v174 offset:5120
	ds_read_b128 v[214:217], v174 offset:6144
	ds_read_b128 v[218:221], v174 offset:7168
	global_load_lds_dwordx4 v164, s[44:45]
	s_add_i32 m0, s14, 0xe000
	s_nop 0
	global_load_lds_dwordx4 v166, s[44:45]
	s_waitcnt vmcnt(8) lgkmcnt(0)
	s_barrier
	v_mfma_f32_16x16x32_bf16 v[142:145], v[82:85], v[184:187], v[142:145]
	v_mfma_f32_16x16x32_bf16 v[138:141], v[98:101], v[184:187], v[138:141]
	v_mfma_f32_16x16x32_bf16 v[126:129], v[82:85], v[192:195], v[126:129]
	v_mfma_f32_16x16x32_bf16 v[122:125], v[98:101], v[192:195], v[122:125]
	v_mfma_f32_16x16x32_bf16 v[110:113], v[82:85], v[200:203], v[110:113]
	v_mfma_f32_16x16x32_bf16 v[106:109], v[98:101], v[200:203], v[106:109]
	v_mfma_f32_16x16x32_bf16 v[78:81], v[82:85], v[214:217], v[78:81]
	v_mfma_f32_16x16x32_bf16 v[74:77], v[98:101], v[214:217], v[74:77]
	v_mfma_f32_16x16x32_bf16 v[142:145], v[86:89], v[188:191], v[142:145]
	v_mfma_f32_16x16x32_bf16 v[138:141], v[102:105], v[188:191], v[138:141]
	v_mfma_f32_16x16x32_bf16 v[126:129], v[86:89], v[196:199], v[126:129]
	v_mfma_f32_16x16x32_bf16 v[122:125], v[102:105], v[196:199], v[122:125]
	v_mfma_f32_16x16x32_bf16 v[110:113], v[86:89], v[210:213], v[110:113]
	v_mfma_f32_16x16x32_bf16 v[106:109], v[102:105], v[210:213], v[106:109]
	v_mfma_f32_16x16x32_bf16 v[78:81], v[86:89], v[218:221], v[78:81]
	v_mfma_f32_16x16x32_bf16 v[74:77], v[102:105], v[218:221], v[74:77]
	v_mfma_f32_16x16x32_bf16 v[134:137], v[154:157], v[184:187], v[134:137]
	v_mfma_f32_16x16x32_bf16 v[130:133], v[176:179], v[184:187], v[130:133]
	v_mfma_f32_16x16x32_bf16 v[118:121], v[154:157], v[192:195], v[118:121]
	v_mfma_f32_16x16x32_bf16 v[114:117], v[176:179], v[192:195], v[114:117]
	v_mfma_f32_16x16x32_bf16 v[94:97], v[154:157], v[200:203], v[94:97]
	v_mfma_f32_16x16x32_bf16 v[90:93], v[176:179], v[200:203], v[90:93]
	v_mfma_f32_16x16x32_bf16 v[70:73], v[154:157], v[214:217], v[70:73]
	v_mfma_f32_16x16x32_bf16 v[66:69], v[176:179], v[214:217], v[66:69]
	v_mfma_f32_16x16x32_bf16 v[134:137], v[168:171], v[188:191], v[134:137]
	v_mfma_f32_16x16x32_bf16 v[130:133], v[180:183], v[188:191], v[130:133]
	v_mfma_f32_16x16x32_bf16 v[118:121], v[168:171], v[196:199], v[118:121]
	v_mfma_f32_16x16x32_bf16 v[114:117], v[180:183], v[196:199], v[114:117]
	v_mfma_f32_16x16x32_bf16 v[94:97], v[168:171], v[210:213], v[94:97]
	v_mfma_f32_16x16x32_bf16 v[90:93], v[180:183], v[210:213], v[90:93]
	v_mfma_f32_16x16x32_bf16 v[70:73], v[168:171], v[218:221], v[70:73]
	v_mfma_f32_16x16x32_bf16 v[66:69], v[180:183], v[218:221], v[66:69]
	s_barrier
	s_add_i32 s58, s58, s5
	s_mov_b32 m0, s58
	ds_read_b128 v[184:187], v174 offset:16384
	ds_read_b128 v[188:191], v174 offset:17408
	ds_read_b128 v[192:195], v174 offset:18432
	ds_read_b128 v[196:199], v174 offset:19456
	ds_read_b128 v[200:203], v174 offset:20480
	ds_read_b128 v[210:213], v174 offset:21504
	ds_read_b128 v[214:217], v174 offset:22528
	ds_read_b128 v[218:221], v174 offset:23552
	global_load_lds_dwordx4 v0, s[46:47]
	s_add_i32 m0, s58, 0x2000
	s_add_u32 s58, s46, 0x80000
	s_addc_u32 s59, s47, 0
	s_add_i32 s60, s60, s5
	global_load_lds_dwordx4 v158, s[46:47]
	s_mov_b32 m0, s60
	s_nop 0
	global_load_lds_dwordx4 v0, s[58:59]
	s_add_i32 m0, s60, 0x2000
	s_nop 0
	global_load_lds_dwordx4 v158, s[58:59]
	s_mov_b32 m0, s14
	s_nop 0
	global_load_lds_dwordx4 v162, s[48:49]
	s_mov_b32 m0, s15
	s_nop 0
	global_load_lds_dwordx4 v160, s[48:49]
	s_add_u32 s98, s46, 0x80
	s_addc_u32 s99, s47, 0
	s_add_u32 s100, s48, 0x80
	s_addc_u32 s101, s49, 0
	s_waitcnt vmcnt(8) lgkmcnt(0)
	s_barrier
	v_mfma_f32_16x16x32_bf16 v[62:65], v[82:85], v[184:187], v[62:65]
	v_mfma_f32_16x16x32_bf16 v[58:61], v[98:101], v[184:187], v[58:61]
	v_mfma_f32_16x16x32_bf16 v[46:49], v[82:85], v[192:195], v[46:49]
	v_mfma_f32_16x16x32_bf16 v[42:45], v[98:101], v[192:195], v[42:45]
	v_mfma_f32_16x16x32_bf16 v[30:33], v[82:85], v[200:203], v[30:33]
	v_mfma_f32_16x16x32_bf16 v[26:29], v[98:101], v[200:203], v[26:29]
	v_mfma_f32_16x16x32_bf16 v[14:17], v[82:85], v[214:217], v[14:17]
	v_mfma_f32_16x16x32_bf16 v[10:13], v[98:101], v[214:217], v[10:13]
	v_mfma_f32_16x16x32_bf16 v[62:65], v[86:89], v[188:191], v[62:65]
	v_mfma_f32_16x16x32_bf16 v[58:61], v[102:105], v[188:191], v[58:61]
	v_mfma_f32_16x16x32_bf16 v[46:49], v[86:89], v[196:199], v[46:49]
	v_mfma_f32_16x16x32_bf16 v[42:45], v[102:105], v[196:199], v[42:45]
	v_mfma_f32_16x16x32_bf16 v[30:33], v[86:89], v[210:213], v[30:33]
	v_mfma_f32_16x16x32_bf16 v[26:29], v[102:105], v[210:213], v[26:29]
	v_mfma_f32_16x16x32_bf16 v[14:17], v[86:89], v[218:221], v[14:17]
	v_mfma_f32_16x16x32_bf16 v[10:13], v[102:105], v[218:221], v[10:13]
	v_mfma_f32_16x16x32_bf16 v[54:57], v[154:157], v[184:187], v[54:57]
	v_mfma_f32_16x16x32_bf16 v[50:53], v[176:179], v[184:187], v[50:53]
	v_mfma_f32_16x16x32_bf16 v[38:41], v[154:157], v[192:195], v[38:41]
	v_mfma_f32_16x16x32_bf16 v[34:37], v[176:179], v[192:195], v[34:37]
	v_mfma_f32_16x16x32_bf16 v[22:25], v[154:157], v[200:203], v[22:25]
	v_mfma_f32_16x16x32_bf16 v[18:21], v[176:179], v[200:203], v[18:21]
	v_mfma_f32_16x16x32_bf16 v[6:9], v[154:157], v[214:217], v[6:9]
	v_mfma_f32_16x16x32_bf16 v[2:5], v[176:179], v[214:217], v[2:5]
	v_mfma_f32_16x16x32_bf16 v[54:57], v[168:171], v[188:191], v[54:57]
	v_mfma_f32_16x16x32_bf16 v[50:53], v[180:183], v[188:191], v[50:53]
	v_mfma_f32_16x16x32_bf16 v[38:41], v[168:171], v[196:199], v[38:41]
	v_mfma_f32_16x16x32_bf16 v[34:37], v[180:183], v[196:199], v[34:37]
	v_mfma_f32_16x16x32_bf16 v[22:25], v[168:171], v[210:213], v[22:25]
	v_mfma_f32_16x16x32_bf16 v[18:21], v[180:183], v[210:213], v[18:21]
	v_mfma_f32_16x16x32_bf16 v[6:9], v[168:171], v[218:221], v[6:9]
	v_mfma_f32_16x16x32_bf16 v[2:5], v[180:183], v[218:221], v[2:5]
	s_barrier
	s_add_i32 s58, 0, 0x18000
	s_add_i32 s59, 0, 0x1c000
	ds_read_b128 v[82:85], v238
	ds_read_b128 v[86:89], v238 offset:1024
	ds_read_b128 v[98:101], v238 offset:2048
	ds_read_b128 v[102:105], v238 offset:3072
	ds_read_b128 v[154:157], v239
	ds_read_b128 v[168:171], v239 offset:1024
	ds_read_b128 v[176:179], v239 offset:2048
	ds_read_b128 v[180:183], v239 offset:3072
	s_add_u32 s48, s48, 0x80000
	s_addc_u32 s49, s49, 0
	s_mov_b32 m0, s16
	ds_read_b128 v[184:187], v174 offset:32768
	ds_read_b128 v[188:191], v174 offset:33792
	ds_read_b128 v[192:195], v174 offset:34816
	ds_read_b128 v[196:199], v174 offset:35840
	ds_read_b128 v[200:203], v174 offset:36864
	ds_read_b128 v[210:213], v174 offset:37888
	ds_read_b128 v[214:217], v174 offset:38912
	ds_read_b128 v[218:221], v174 offset:39936
	global_load_lds_dwordx4 v162, s[48:49]
	s_mov_b32 m0, s18
	s_nop 0
	global_load_lds_dwordx4 v160, s[48:49]
	s_waitcnt vmcnt(8) lgkmcnt(0)
	s_barrier
	v_mfma_f32_16x16x32_bf16 v[142:145], v[82:85], v[184:187], v[142:145]
	v_mfma_f32_16x16x32_bf16 v[138:141], v[98:101], v[184:187], v[138:141]
	v_mfma_f32_16x16x32_bf16 v[126:129], v[82:85], v[192:195], v[126:129]
	v_mfma_f32_16x16x32_bf16 v[122:125], v[98:101], v[192:195], v[122:125]
	v_mfma_f32_16x16x32_bf16 v[110:113], v[82:85], v[200:203], v[110:113]
	v_mfma_f32_16x16x32_bf16 v[106:109], v[98:101], v[200:203], v[106:109]
	v_mfma_f32_16x16x32_bf16 v[78:81], v[82:85], v[214:217], v[78:81]
	v_mfma_f32_16x16x32_bf16 v[74:77], v[98:101], v[214:217], v[74:77]
	v_mfma_f32_16x16x32_bf16 v[142:145], v[86:89], v[188:191], v[142:145]
	v_mfma_f32_16x16x32_bf16 v[138:141], v[102:105], v[188:191], v[138:141]
	v_mfma_f32_16x16x32_bf16 v[126:129], v[86:89], v[196:199], v[126:129]
	v_mfma_f32_16x16x32_bf16 v[122:125], v[102:105], v[196:199], v[122:125]
	v_mfma_f32_16x16x32_bf16 v[110:113], v[86:89], v[210:213], v[110:113]
	v_mfma_f32_16x16x32_bf16 v[106:109], v[102:105], v[210:213], v[106:109]
	v_mfma_f32_16x16x32_bf16 v[78:81], v[86:89], v[218:221], v[78:81]
	v_mfma_f32_16x16x32_bf16 v[74:77], v[102:105], v[218:221], v[74:77]
	v_mfma_f32_16x16x32_bf16 v[134:137], v[154:157], v[184:187], v[134:137]
	v_mfma_f32_16x16x32_bf16 v[130:133], v[176:179], v[184:187], v[130:133]
	v_mfma_f32_16x16x32_bf16 v[118:121], v[154:157], v[192:195], v[118:121]
	v_mfma_f32_16x16x32_bf16 v[114:117], v[176:179], v[192:195], v[114:117]
	v_mfma_f32_16x16x32_bf16 v[94:97], v[154:157], v[200:203], v[94:97]
	v_mfma_f32_16x16x32_bf16 v[90:93], v[176:179], v[200:203], v[90:93]
	v_mfma_f32_16x16x32_bf16 v[70:73], v[154:157], v[214:217], v[70:73]
	v_mfma_f32_16x16x32_bf16 v[66:69], v[176:179], v[214:217], v[66:69]
	v_mfma_f32_16x16x32_bf16 v[134:137], v[168:171], v[188:191], v[134:137]
	v_mfma_f32_16x16x32_bf16 v[130:133], v[180:183], v[188:191], v[130:133]
	v_mfma_f32_16x16x32_bf16 v[118:121], v[168:171], v[196:199], v[118:121]
	v_mfma_f32_16x16x32_bf16 v[114:117], v[180:183], v[196:199], v[114:117]
	v_mfma_f32_16x16x32_bf16 v[94:97], v[168:171], v[210:213], v[94:97]
	v_mfma_f32_16x16x32_bf16 v[90:93], v[180:183], v[210:213], v[90:93]
	v_mfma_f32_16x16x32_bf16 v[70:73], v[168:171], v[218:221], v[70:73]
	v_mfma_f32_16x16x32_bf16 v[66:69], v[180:183], v[218:221], v[66:69]
	s_barrier
	s_add_i32 s48, s58, s5
	s_mov_b32 m0, s48
	ds_read_b128 v[184:187], v174 offset:49152
	ds_read_b128 v[188:191], v174 offset:50176
	ds_read_b128 v[192:195], v174 offset:51200
	ds_read_b128 v[196:199], v174 offset:52224
	ds_read_b128 v[200:203], v174 offset:53248
	ds_read_b128 v[210:213], v174 offset:54272
	ds_read_b128 v[214:217], v174 offset:55296
	ds_read_b128 v[218:221], v174 offset:56320
	global_load_lds_dwordx4 v0, s[98:99]
	s_add_i32 m0, s48, 0x2000
	s_add_u32 s46, s46, 0x80080
	s_addc_u32 s47, s47, 0
	s_add_i32 s48, s59, s5
	global_load_lds_dwordx4 v158, s[98:99]
	s_mov_b32 m0, s48
	s_nop 0
	global_load_lds_dwordx4 v0, s[46:47]
	s_add_i32 m0, s48, 0x2000
	s_nop 0
	global_load_lds_dwordx4 v158, s[46:47]
	s_mov_b32 m0, s25
	s_nop 0
	global_load_lds_dwordx4 v162, s[100:101]
	s_mov_b32 m0, s33
	s_nop 0
	global_load_lds_dwordx4 v160, s[100:101]
	s_waitcnt vmcnt(8) lgkmcnt(0)
	s_barrier
	v_mfma_f32_16x16x32_bf16 v[62:65], v[82:85], v[184:187], v[62:65]
	v_mfma_f32_16x16x32_bf16 v[58:61], v[98:101], v[184:187], v[58:61]
	v_mfma_f32_16x16x32_bf16 v[46:49], v[82:85], v[192:195], v[46:49]
	v_mfma_f32_16x16x32_bf16 v[42:45], v[98:101], v[192:195], v[42:45]
	v_mfma_f32_16x16x32_bf16 v[30:33], v[82:85], v[200:203], v[30:33]
	v_mfma_f32_16x16x32_bf16 v[26:29], v[98:101], v[200:203], v[26:29]
	v_mfma_f32_16x16x32_bf16 v[14:17], v[82:85], v[214:217], v[14:17]
	v_mfma_f32_16x16x32_bf16 v[10:13], v[98:101], v[214:217], v[10:13]
	v_mfma_f32_16x16x32_bf16 v[62:65], v[86:89], v[188:191], v[62:65]
	v_mfma_f32_16x16x32_bf16 v[58:61], v[102:105], v[188:191], v[58:61]
	v_mfma_f32_16x16x32_bf16 v[46:49], v[86:89], v[196:199], v[46:49]
	v_mfma_f32_16x16x32_bf16 v[42:45], v[102:105], v[196:199], v[42:45]
	v_mfma_f32_16x16x32_bf16 v[30:33], v[86:89], v[210:213], v[30:33]
	v_mfma_f32_16x16x32_bf16 v[26:29], v[102:105], v[210:213], v[26:29]
	v_mfma_f32_16x16x32_bf16 v[14:17], v[86:89], v[218:221], v[14:17]
	v_mfma_f32_16x16x32_bf16 v[10:13], v[102:105], v[218:221], v[10:13]
	v_mfma_f32_16x16x32_bf16 v[54:57], v[154:157], v[184:187], v[54:57]
	v_mfma_f32_16x16x32_bf16 v[50:53], v[176:179], v[184:187], v[50:53]
	v_mfma_f32_16x16x32_bf16 v[38:41], v[154:157], v[192:195], v[38:41]
	v_mfma_f32_16x16x32_bf16 v[34:37], v[176:179], v[192:195], v[34:37]
	v_mfma_f32_16x16x32_bf16 v[22:25], v[154:157], v[200:203], v[22:25]
	v_mfma_f32_16x16x32_bf16 v[18:21], v[176:179], v[200:203], v[18:21]
	v_mfma_f32_16x16x32_bf16 v[6:9], v[154:157], v[214:217], v[6:9]
	v_mfma_f32_16x16x32_bf16 v[2:5], v[176:179], v[214:217], v[2:5]
	v_mfma_f32_16x16x32_bf16 v[54:57], v[168:171], v[188:191], v[54:57]
	v_mfma_f32_16x16x32_bf16 v[50:53], v[180:183], v[188:191], v[50:53]
	v_mfma_f32_16x16x32_bf16 v[38:41], v[168:171], v[196:199], v[38:41]
	v_mfma_f32_16x16x32_bf16 v[34:37], v[180:183], v[196:199], v[34:37]
	v_mfma_f32_16x16x32_bf16 v[22:25], v[168:171], v[210:213], v[22:25]
	v_mfma_f32_16x16x32_bf16 v[18:21], v[180:183], v[210:213], v[18:21]
	v_mfma_f32_16x16x32_bf16 v[6:9], v[168:171], v[218:221], v[6:9]
	v_mfma_f32_16x16x32_bf16 v[2:5], v[180:183], v[218:221], v[2:5]
	s_add_i32 s57, s57, 2
	s_add_u32 s44, s44, 0x100
	s_addc_u32 s45, s45, 0
	s_add_u32 s55, s55, 0x100
	s_addc_u32 s56, s56, 0
	s_add_u32 s46, s44, 0xfff80080
	s_addc_u32 s47, s45, -1
	s_add_i32 s58, 0, 0x10000
	s_cmp_eq_u32 s57, 28
	s_cselect_b32 s49, s21, s47
	s_cselect_b32 s48, s50, s46
	s_cselect_b32 s47, s13, s56
	s_cselect_b32 s46, s51, s55
	s_add_i32 s60, 0, 0x14000
	s_cmp_gt_u32 s57, 29
	s_barrier
	s_cbranch_scc0 .LBB0_516
	s_setprio 0
	s_and_b64 vcc, exec, s[10:11]
	s_cbranch_vccz .LBB0_519
	s_barrier

.Lgprio2:
	v_add_u32_e32 v236, 0x10000, v175
	v_add_u32_e32 v237, 0x14000, v175
	v_add_u32_e32 v238, 0x18000, v175
	v_add_u32_e32 v239, 0x1c000, v175
	s_add_u32 s22, s6, 0xfff80080
	s_addc_u32 s23, s7, -1
	s_add_i32 s54, 0, 0x10000
	s_cmp_eq_u32 s53, 28
	s_cselect_b32 s47, s18, s23
	s_cselect_b32 s46, s19, s22
	s_cselect_b32 s23, s21, s52
	s_cselect_b32 s22, s25, s41
	s_add_i32 s56, 0, 0x14000
.LBB0_604:
	ds_read_b128 v[130:133], v236
	ds_read_b128 v[134:137], v236 offset:1024
	ds_read_b128 v[154:157], v236 offset:2048
	ds_read_b128 v[162:165], v236 offset:3072
	ds_read_b128 v[166:169], v237
	ds_read_b128 v[170:173], v237 offset:1024
	ds_read_b128 v[180:183], v237 offset:2048
	ds_read_b128 v[184:187], v237 offset:3072
	s_add_i32 m0, s16, 0xc000
	ds_read_b128 v[188:191], v179
	ds_read_b128 v[192:195], v179 offset:1024
	ds_read_b128 v[196:199], v179 offset:2048
	ds_read_b128 v[200:203], v179 offset:3072
	ds_read_b128 v[210:213], v179 offset:4096
	ds_read_b128 v[214:217], v179 offset:5120
	ds_read_b128 v[218:221], v179 offset:6144
	ds_read_b128 v[222:225], v179 offset:7168
	global_load_lds_dwordx4 v158, s[6:7]
	s_add_i32 m0, s16, 0xe000
	s_nop 0
	global_load_lds_dwordx4 v160, s[6:7]
	s_waitcnt vmcnt(8) lgkmcnt(0)
	s_barrier
	v_mfma_f32_16x16x32_bf16 v[126:129], v[130:133], v[188:191], v[126:129]
	v_mfma_f32_16x16x32_bf16 v[122:125], v[154:157], v[188:191], v[122:125]
	v_mfma_f32_16x16x32_bf16 v[110:113], v[130:133], v[196:199], v[110:113]
	v_mfma_f32_16x16x32_bf16 v[106:109], v[154:157], v[196:199], v[106:109]
	v_mfma_f32_16x16x32_bf16 v[94:97], v[130:133], v[210:213], v[94:97]
	v_mfma_f32_16x16x32_bf16 v[90:93], v[154:157], v[210:213], v[90:93]
	v_mfma_f32_16x16x32_bf16 v[78:81], v[130:133], v[218:221], v[78:81]
	v_mfma_f32_16x16x32_bf16 v[74:77], v[154:157], v[218:221], v[74:77]
	v_mfma_f32_16x16x32_bf16 v[126:129], v[134:137], v[192:195], v[126:129]
	v_mfma_f32_16x16x32_bf16 v[122:125], v[162:165], v[192:195], v[122:125]
	v_mfma_f32_16x16x32_bf16 v[110:113], v[134:137], v[200:203], v[110:113]
	v_mfma_f32_16x16x32_bf16 v[106:109], v[162:165], v[200:203], v[106:109]
	v_mfma_f32_16x16x32_bf16 v[94:97], v[134:137], v[214:217], v[94:97]
	v_mfma_f32_16x16x32_bf16 v[90:93], v[162:165], v[214:217], v[90:93]
	v_mfma_f32_16x16x32_bf16 v[78:81], v[134:137], v[222:225], v[78:81]
	v_mfma_f32_16x16x32_bf16 v[74:77], v[162:165], v[222:225], v[74:77]
	v_mfma_f32_16x16x32_bf16 v[118:121], v[166:169], v[188:191], v[118:121]
	v_mfma_f32_16x16x32_bf16 v[114:117], v[180:183], v[188:191], v[114:117]
	v_mfma_f32_16x16x32_bf16 v[102:105], v[166:169], v[196:199], v[102:105]
	v_mfma_f32_16x16x32_bf16 v[98:101], v[180:183], v[196:199], v[98:101]
	v_mfma_f32_16x16x32_bf16 v[86:89], v[166:169], v[210:213], v[86:89]
	v_mfma_f32_16x16x32_bf16 v[82:85], v[180:183], v[210:213], v[82:85]
	v_mfma_f32_16x16x32_bf16 v[70:73], v[166:169], v[218:221], v[70:73]
	v_mfma_f32_16x16x32_bf16 v[66:69], v[180:183], v[218:221], v[66:69]
	v_mfma_f32_16x16x32_bf16 v[118:121], v[170:173], v[192:195], v[118:121]
	v_mfma_f32_16x16x32_bf16 v[114:117], v[184:187], v[192:195], v[114:117]
	v_mfma_f32_16x16x32_bf16 v[102:105], v[170:173], v[200:203], v[102:105]
	v_mfma_f32_16x16x32_bf16 v[98:101], v[184:187], v[200:203], v[98:101]
	v_mfma_f32_16x16x32_bf16 v[86:89], v[170:173], v[214:217], v[86:89]
	v_mfma_f32_16x16x32_bf16 v[82:85], v[184:187], v[214:217], v[82:85]
	v_mfma_f32_16x16x32_bf16 v[70:73], v[170:173], v[222:225], v[70:73]
	v_mfma_f32_16x16x32_bf16 v[66:69], v[184:187], v[222:225], v[66:69]
	s_barrier
	s_add_i32 s54, s54, s15
	s_mov_b32 m0, s54
	ds_read_b128 v[188:191], v179 offset:16384
	ds_read_b128 v[192:195], v179 offset:17408
	ds_read_b128 v[196:199], v179 offset:18432
	ds_read_b128 v[200:203], v179 offset:19456
	ds_read_b128 v[210:213], v179 offset:20480
	ds_read_b128 v[214:217], v179 offset:21504
	ds_read_b128 v[218:221], v179 offset:22528
	ds_read_b128 v[222:225], v179 offset:23552
	global_load_lds_dwordx4 v142, s[22:23]
	s_add_i32 m0, s54, 0x2000
	s_add_u32 s54, s22, 0x80000
	s_addc_u32 s55, s23, 0
	s_add_i32 s56, s56, s15
	global_load_lds_dwordx4 v138, s[22:23]
	s_mov_b32 m0, s56
	s_nop 0
	global_load_lds_dwordx4 v142, s[54:55]
	s_add_i32 m0, s56, 0x2000
	s_nop 0
	global_load_lds_dwordx4 v138, s[54:55]
	s_mov_b32 m0, s16
	s_nop 0
	global_load_lds_dwordx4 v144, s[46:47]
	s_mov_b32 m0, s33
	s_nop 0
	global_load_lds_dwordx4 v140, s[46:47]
	s_add_u32 s98, s22, 0x80
	s_addc_u32 s99, s23, 0
	s_add_u32 s100, s46, 0x80
	s_addc_u32 s101, s47, 0
	s_waitcnt vmcnt(8) lgkmcnt(0)
	s_barrier
	v_mfma_f32_16x16x32_bf16 v[62:65], v[130:133], v[188:191], v[62:65]
	v_mfma_f32_16x16x32_bf16 v[58:61], v[154:157], v[188:191], v[58:61]
	v_mfma_f32_16x16x32_bf16 v[46:49], v[130:133], v[196:199], v[46:49]
	v_mfma_f32_16x16x32_bf16 v[42:45], v[154:157], v[196:199], v[42:45]
	v_mfma_f32_16x16x32_bf16 v[30:33], v[130:133], v[210:213], v[30:33]
	v_mfma_f32_16x16x32_bf16 v[26:29], v[154:157], v[210:213], v[26:29]
	v_mfma_f32_16x16x32_bf16 v[14:17], v[130:133], v[218:221], v[14:17]
	v_mfma_f32_16x16x32_bf16 v[10:13], v[154:157], v[218:221], v[10:13]
	v_mfma_f32_16x16x32_bf16 v[62:65], v[134:137], v[192:195], v[62:65]
	v_mfma_f32_16x16x32_bf16 v[58:61], v[162:165], v[192:195], v[58:61]
	v_mfma_f32_16x16x32_bf16 v[46:49], v[134:137], v[200:203], v[46:49]
	v_mfma_f32_16x16x32_bf16 v[42:45], v[162:165], v[200:203], v[42:45]
	v_mfma_f32_16x16x32_bf16 v[30:33], v[134:137], v[214:217], v[30:33]
	v_mfma_f32_16x16x32_bf16 v[26:29], v[162:165], v[214:217], v[26:29]
	v_mfma_f32_16x16x32_bf16 v[14:17], v[134:137], v[222:225], v[14:17]
	v_mfma_f32_16x16x32_bf16 v[10:13], v[162:165], v[222:225], v[10:13]
	v_mfma_f32_16x16x32_bf16 v[54:57], v[166:169], v[188:191], v[54:57]
	v_mfma_f32_16x16x32_bf16 v[50:53], v[180:183], v[188:191], v[50:53]
	v_mfma_f32_16x16x32_bf16 v[38:41], v[166:169], v[196:199], v[38:41]
	v_mfma_f32_16x16x32_bf16 v[34:37], v[180:183], v[196:199], v[34:37]
	v_mfma_f32_16x16x32_bf16 v[22:25], v[166:169], v[210:213], v[22:25]
	v_mfma_f32_16x16x32_bf16 v[18:21], v[180:183], v[210:213], v[18:21]
	v_mfma_f32_16x16x32_bf16 v[6:9], v[166:169], v[218:221], v[6:9]
	v_mfma_f32_16x16x32_bf16 v[2:5], v[180:183], v[218:221], v[2:5]
	v_mfma_f32_16x16x32_bf16 v[54:57], v[170:173], v[192:195], v[54:57]
	v_mfma_f32_16x16x32_bf16 v[50:53], v[184:187], v[192:195], v[50:53]
	v_mfma_f32_16x16x32_bf16 v[38:41], v[170:173], v[200:203], v[38:41]
	v_mfma_f32_16x16x32_bf16 v[34:37], v[184:187], v[200:203], v[34:37]
	v_mfma_f32_16x16x32_bf16 v[22:25], v[170:173], v[214:217], v[22:25]
	v_mfma_f32_16x16x32_bf16 v[18:21], v[184:187], v[214:217], v[18:21]
	v_mfma_f32_16x16x32_bf16 v[6:9], v[170:173], v[222:225], v[6:9]
	v_mfma_f32_16x16x32_bf16 v[2:5], v[184:187], v[222:225], v[2:5]
	s_barrier
	s_add_i32 s54, 0, 0x18000
	s_add_i32 s55, 0, 0x1c000
	ds_read_b128 v[130:133], v238
	ds_read_b128 v[134:137], v238 offset:1024
	ds_read_b128 v[154:157], v238 offset:2048
	ds_read_b128 v[162:165], v238 offset:3072
	ds_read_b128 v[166:169], v239
	ds_read_b128 v[170:173], v239 offset:1024
	ds_read_b128 v[180:183], v239 offset:2048
	ds_read_b128 v[184:187], v239 offset:3072
	s_add_u32 s46, s46, 0x80000
	s_addc_u32 s47, s47, 0
	s_mov_b32 m0, s37
	ds_read_b128 v[188:191], v179 offset:32768
	ds_read_b128 v[192:195], v179 offset:33792
	ds_read_b128 v[196:199], v179 offset:34816
	ds_read_b128 v[200:203], v179 offset:35840
	ds_read_b128 v[210:213], v179 offset:36864
	ds_read_b128 v[214:217], v179 offset:37888
	ds_read_b128 v[218:221], v179 offset:38912
	ds_read_b128 v[222:225], v179 offset:39936
	global_load_lds_dwordx4 v144, s[46:47]
	s_mov_b32 m0, s48
	s_nop 0
	global_load_lds_dwordx4 v140, s[46:47]
	s_waitcnt vmcnt(8) lgkmcnt(0)
	s_barrier
	v_mfma_f32_16x16x32_bf16 v[126:129], v[130:133], v[188:191], v[126:129]
	v_mfma_f32_16x16x32_bf16 v[122:125], v[154:157], v[188:191], v[122:125]
	v_mfma_f32_16x16x32_bf16 v[110:113], v[130:133], v[196:199], v[110:113]
	v_mfma_f32_16x16x32_bf16 v[106:109], v[154:157], v[196:199], v[106:109]
	v_mfma_f32_16x16x32_bf16 v[94:97], v[130:133], v[210:213], v[94:97]
	v_mfma_f32_16x16x32_bf16 v[90:93], v[154:157], v[210:213], v[90:93]
	v_mfma_f32_16x16x32_bf16 v[78:81], v[130:133], v[218:221], v[78:81]
	v_mfma_f32_16x16x32_bf16 v[74:77], v[154:157], v[218:221], v[74:77]
	v_mfma_f32_16x16x32_bf16 v[126:129], v[134:137], v[192:195], v[126:129]
	v_mfma_f32_16x16x32_bf16 v[122:125], v[162:165], v[192:195], v[122:125]
	v_mfma_f32_16x16x32_bf16 v[110:113], v[134:137], v[200:203], v[110:113]
	v_mfma_f32_16x16x32_bf16 v[106:109], v[162:165], v[200:203], v[106:109]
	v_mfma_f32_16x16x32_bf16 v[94:97], v[134:137], v[214:217], v[94:97]
	v_mfma_f32_16x16x32_bf16 v[90:93], v[162:165], v[214:217], v[90:93]
	v_mfma_f32_16x16x32_bf16 v[78:81], v[134:137], v[222:225], v[78:81]
	v_mfma_f32_16x16x32_bf16 v[74:77], v[162:165], v[222:225], v[74:77]
	v_mfma_f32_16x16x32_bf16 v[118:121], v[166:169], v[188:191], v[118:121]
	v_mfma_f32_16x16x32_bf16 v[114:117], v[180:183], v[188:191], v[114:117]
	v_mfma_f32_16x16x32_bf16 v[102:105], v[166:169], v[196:199], v[102:105]
	v_mfma_f32_16x16x32_bf16 v[98:101], v[180:183], v[196:199], v[98:101]
	v_mfma_f32_16x16x32_bf16 v[86:89], v[166:169], v[210:213], v[86:89]
	v_mfma_f32_16x16x32_bf16 v[82:85], v[180:183], v[210:213], v[82:85]
	v_mfma_f32_16x16x32_bf16 v[70:73], v[166:169], v[218:221], v[70:73]
	v_mfma_f32_16x16x32_bf16 v[66:69], v[180:183], v[218:221], v[66:69]
	v_mfma_f32_16x16x32_bf16 v[118:121], v[170:173], v[192:195], v[118:121]
	v_mfma_f32_16x16x32_bf16 v[114:117], v[184:187], v[192:195], v[114:117]
	v_mfma_f32_16x16x32_bf16 v[102:105], v[170:173], v[200:203], v[102:105]
	v_mfma_f32_16x16x32_bf16 v[98:101], v[184:187], v[200:203], v[98:101]
	v_mfma_f32_16x16x32_bf16 v[86:89], v[170:173], v[214:217], v[86:89]
	v_mfma_f32_16x16x32_bf16 v[82:85], v[184:187], v[214:217], v[82:85]
	v_mfma_f32_16x16x32_bf16 v[70:73], v[170:173], v[222:225], v[70:73]
	v_mfma_f32_16x16x32_bf16 v[66:69], v[184:187], v[222:225], v[66:69]
	s_barrier
	s_add_i32 s46, s54, s15
	s_mov_b32 m0, s46
	ds_read_b128 v[188:191], v179 offset:49152
	ds_read_b128 v[192:195], v179 offset:50176
	ds_read_b128 v[196:199], v179 offset:51200
	ds_read_b128 v[200:203], v179 offset:52224
	ds_read_b128 v[210:213], v179 offset:53248
	ds_read_b128 v[214:217], v179 offset:54272
	ds_read_b128 v[218:221], v179 offset:55296
	ds_read_b128 v[222:225], v179 offset:56320
	global_load_lds_dwordx4 v142, s[98:99]
	s_add_i32 m0, s46, 0x2000
	s_add_u32 s22, s22, 0x80080
	s_addc_u32 s23, s23, 0
	s_add_i32 s46, s55, s15
	global_load_lds_dwordx4 v138, s[98:99]
	s_mov_b32 m0, s46
	s_nop 0
	global_load_lds_dwordx4 v142, s[22:23]
	s_add_i32 m0, s46, 0x2000
	s_nop 0
	global_load_lds_dwordx4 v138, s[22:23]
	s_mov_b32 m0, s49
	s_nop 0
	global_load_lds_dwordx4 v144, s[100:101]
	s_mov_b32 m0, s50
	s_nop 0
	global_load_lds_dwordx4 v140, s[100:101]
	s_waitcnt vmcnt(8) lgkmcnt(0)
	s_barrier
	v_mfma_f32_16x16x32_bf16 v[62:65], v[130:133], v[188:191], v[62:65]
	v_mfma_f32_16x16x32_bf16 v[58:61], v[154:157], v[188:191], v[58:61]
	v_mfma_f32_16x16x32_bf16 v[46:49], v[130:133], v[196:199], v[46:49]
	v_mfma_f32_16x16x32_bf16 v[42:45], v[154:157], v[196:199], v[42:45]
	v_mfma_f32_16x16x32_bf16 v[30:33], v[130:133], v[210:213], v[30:33]
	v_mfma_f32_16x16x32_bf16 v[26:29], v[154:157], v[210:213], v[26:29]
	v_mfma_f32_16x16x32_bf16 v[14:17], v[130:133], v[218:221], v[14:17]
	v_mfma_f32_16x16x32_bf16 v[10:13], v[154:157], v[218:221], v[10:13]
	v_mfma_f32_16x16x32_bf16 v[62:65], v[134:137], v[192:195], v[62:65]
	v_mfma_f32_16x16x32_bf16 v[58:61], v[162:165], v[192:195], v[58:61]
	v_mfma_f32_16x16x32_bf16 v[46:49], v[134:137], v[200:203], v[46:49]
	v_mfma_f32_16x16x32_bf16 v[42:45], v[162:165], v[200:203], v[42:45]
	v_mfma_f32_16x16x32_bf16 v[30:33], v[134:137], v[214:217], v[30:33]
	v_mfma_f32_16x16x32_bf16 v[26:29], v[162:165], v[214:217], v[26:29]
	v_mfma_f32_16x16x32_bf16 v[14:17], v[134:137], v[222:225], v[14:17]
	v_mfma_f32_16x16x32_bf16 v[10:13], v[162:165], v[222:225], v[10:13]
	v_mfma_f32_16x16x32_bf16 v[54:57], v[166:169], v[188:191], v[54:57]
	v_mfma_f32_16x16x32_bf16 v[50:53], v[180:183], v[188:191], v[50:53]
	v_mfma_f32_16x16x32_bf16 v[38:41], v[166:169], v[196:199], v[38:41]
	v_mfma_f32_16x16x32_bf16 v[34:37], v[180:183], v[196:199], v[34:37]
	v_mfma_f32_16x16x32_bf16 v[22:25], v[166:169], v[210:213], v[22:25]
	v_mfma_f32_16x16x32_bf16 v[18:21], v[180:183], v[210:213], v[18:21]
	v_mfma_f32_16x16x32_bf16 v[6:9], v[166:169], v[218:221], v[6:9]
	v_mfma_f32_16x16x32_bf16 v[2:5], v[180:183], v[218:221], v[2:5]
	v_mfma_f32_16x16x32_bf16 v[54:57], v[170:173], v[192:195], v[54:57]
	v_mfma_f32_16x16x32_bf16 v[50:53], v[184:187], v[192:195], v[50:53]
	v_mfma_f32_16x16x32_bf16 v[38:41], v[170:173], v[200:203], v[38:41]
	v_mfma_f32_16x16x32_bf16 v[34:37], v[184:187], v[200:203], v[34:37]
	v_mfma_f32_16x16x32_bf16 v[22:25], v[170:173], v[214:217], v[22:25]
	v_mfma_f32_16x16x32_bf16 v[18:21], v[184:187], v[214:217], v[18:21]
	v_mfma_f32_16x16x32_bf16 v[6:9], v[170:173], v[222:225], v[6:9]
	v_mfma_f32_16x16x32_bf16 v[2:5], v[184:187], v[222:225], v[2:5]
	s_add_i32 s53, s53, 2
	s_add_u32 s6, s6, 0x100
	s_addc_u32 s7, s7, 0
	s_add_u32 s41, s41, 0x100
	s_addc_u32 s52, s52, 0
	s_add_u32 s22, s6, 0xfff80080
	s_addc_u32 s23, s7, -1
	s_add_i32 s54, 0, 0x10000
	s_cmp_eq_u32 s53, 28
	s_cselect_b32 s47, s18, s23
	s_cselect_b32 s46, s19, s22
	s_cselect_b32 s23, s21, s52
	s_cselect_b32 s22, s25, s41
	s_add_i32 s56, 0, 0x14000
	s_cmp_gt_u32 s53, 29
	s_barrier
	s_cbranch_scc0 .LBB0_604
	s_setprio 0
	s_and_b64 vcc, exec, s[12:13]
	s_cbranch_vccz .LBB0_607
	s_barrier

.LBB0_728:
	s_add_u32 s42, s22, 0x100
	s_addc_u32 s43, s23, 0
	s_add_i32 s50, 0, 0x10000
	s_cmpk_eq_i32 s25, 0x54
	s_cselect_b32 s49, s21, s43
	s_cselect_b32 s48, s20, s42
	s_cselect_b32 s47, s45, s19
	s_cselect_b32 s46, s44, s18
	s_add_i32 s51, 0, 0x14000
	ds_read_b128 v[42:45], v236
	ds_read_b128 v[46:49], v236 offset:1024
	ds_read_b128 v[50:53], v236 offset:2048
	ds_read_b128 v[54:57], v236 offset:3072
	ds_read_b128 v[154:157], v237
	ds_read_b128 v[168:171], v237 offset:1024
	ds_read_b128 v[172:175], v237 offset:2048
	ds_read_b128 v[180:183], v237 offset:3072
	s_add_i32 m0, s33, 0xc000
	ds_read_b128 v[184:187], v178
	ds_read_b128 v[188:191], v178 offset:1024
	ds_read_b128 v[192:195], v178 offset:2048
	ds_read_b128 v[196:199], v178 offset:3072
	ds_read_b128 v[200:203], v178 offset:4096
	ds_read_b128 v[210:213], v178 offset:5120
	ds_read_b128 v[214:217], v178 offset:6144
	ds_read_b128 v[218:221], v178 offset:7168
	global_load_lds_dwordx4 v164, s[22:23]
	s_add_i32 m0, s33, 0xe000
	s_nop 0
	global_load_lds_dwordx4 v166, s[22:23]
	s_waitcnt vmcnt(8) lgkmcnt(0)
	s_barrier
	v_mfma_f32_16x16x32_bf16 v[142:145], v[42:45], v[184:187], v[142:145]
	v_mfma_f32_16x16x32_bf16 v[138:141], v[50:53], v[184:187], v[138:141]
	v_mfma_f32_16x16x32_bf16 v[126:129], v[42:45], v[192:195], v[126:129]
	v_mfma_f32_16x16x32_bf16 v[122:125], v[50:53], v[192:195], v[122:125]
	v_mfma_f32_16x16x32_bf16 v[110:113], v[42:45], v[200:203], v[110:113]
	v_mfma_f32_16x16x32_bf16 v[106:109], v[50:53], v[200:203], v[106:109]
	v_mfma_f32_16x16x32_bf16 v[94:97], v[42:45], v[214:217], v[94:97]
	v_mfma_f32_16x16x32_bf16 v[90:93], v[50:53], v[214:217], v[90:93]
	v_mfma_f32_16x16x32_bf16 v[142:145], v[46:49], v[188:191], v[142:145]
	v_mfma_f32_16x16x32_bf16 v[138:141], v[54:57], v[188:191], v[138:141]
	v_mfma_f32_16x16x32_bf16 v[126:129], v[46:49], v[196:199], v[126:129]
	v_mfma_f32_16x16x32_bf16 v[122:125], v[54:57], v[196:199], v[122:125]
	v_mfma_f32_16x16x32_bf16 v[110:113], v[46:49], v[210:213], v[110:113]
	v_mfma_f32_16x16x32_bf16 v[106:109], v[54:57], v[210:213], v[106:109]
	v_mfma_f32_16x16x32_bf16 v[94:97], v[46:49], v[218:221], v[94:97]
	v_mfma_f32_16x16x32_bf16 v[90:93], v[54:57], v[218:221], v[90:93]
	v_mfma_f32_16x16x32_bf16 v[134:137], v[154:157], v[184:187], v[134:137]
	v_mfma_f32_16x16x32_bf16 v[130:133], v[172:175], v[184:187], v[130:133]
	v_mfma_f32_16x16x32_bf16 v[118:121], v[154:157], v[192:195], v[118:121]
	v_mfma_f32_16x16x32_bf16 v[114:117], v[172:175], v[192:195], v[114:117]
	v_mfma_f32_16x16x32_bf16 v[102:105], v[154:157], v[200:203], v[102:105]
	v_mfma_f32_16x16x32_bf16 v[98:101], v[172:175], v[200:203], v[98:101]
	v_mfma_f32_16x16x32_bf16 v[86:89], v[154:157], v[214:217], v[86:89]
	v_mfma_f32_16x16x32_bf16 v[82:85], v[172:175], v[214:217], v[82:85]
	v_mfma_f32_16x16x32_bf16 v[134:137], v[168:171], v[188:191], v[134:137]
	v_mfma_f32_16x16x32_bf16 v[130:133], v[180:183], v[188:191], v[130:133]
	v_mfma_f32_16x16x32_bf16 v[118:121], v[168:171], v[196:199], v[118:121]
	v_mfma_f32_16x16x32_bf16 v[114:117], v[180:183], v[196:199], v[114:117]
	v_mfma_f32_16x16x32_bf16 v[102:105], v[168:171], v[210:213], v[102:105]
	v_mfma_f32_16x16x32_bf16 v[98:101], v[180:183], v[210:213], v[98:101]
	v_mfma_f32_16x16x32_bf16 v[86:89], v[168:171], v[218:221], v[86:89]
	v_mfma_f32_16x16x32_bf16 v[82:85], v[180:183], v[218:221], v[82:85]
	s_barrier
	s_add_i32 s22, s50, s16
	s_mov_b32 m0, s22
	ds_read_b128 v[184:187], v178 offset:16384
	ds_read_b128 v[188:191], v178 offset:17408
	ds_read_b128 v[192:195], v178 offset:18432
	ds_read_b128 v[196:199], v178 offset:19456
	ds_read_b128 v[200:203], v178 offset:20480
	ds_read_b128 v[210:213], v178 offset:21504
	ds_read_b128 v[214:217], v178 offset:22528
	ds_read_b128 v[218:221], v178 offset:23552
	global_load_lds_dwordx4 v0, s[46:47]
	s_add_i32 m0, s22, 0x2000
	s_add_u32 s22, s46, 0x160000
	s_addc_u32 s23, s47, 0
	s_add_i32 s50, s51, s16
	global_load_lds_dwordx4 v158, s[46:47]
	s_mov_b32 m0, s50
	s_nop 0
	global_load_lds_dwordx4 v0, s[22:23]
	s_add_i32 m0, s50, 0x2000
	s_nop 0
	global_load_lds_dwordx4 v158, s[22:23]
	s_mov_b32 m0, s33
	s_nop 0
	global_load_lds_dwordx4 v162, s[48:49]
	s_mov_b32 m0, s37
	s_nop 0
	global_load_lds_dwordx4 v160, s[48:49]
	s_add_u32 s98, s46, 0x80
	s_addc_u32 s99, s47, 0
	s_add_u32 s100, s48, 0x80
	s_addc_u32 s101, s49, 0
	s_waitcnt vmcnt(8) lgkmcnt(0)
	s_barrier
	v_mfma_f32_16x16x32_bf16 v[78:81], v[42:45], v[184:187], v[78:81]
	v_mfma_f32_16x16x32_bf16 v[74:77], v[50:53], v[184:187], v[74:77]
	v_mfma_f32_16x16x32_bf16 v[62:65], v[42:45], v[192:195], v[62:65]
	v_mfma_f32_16x16x32_bf16 v[58:61], v[50:53], v[192:195], v[58:61]
	v_mfma_f32_16x16x32_bf16 v[30:33], v[42:45], v[200:203], v[30:33]
	v_mfma_f32_16x16x32_bf16 v[26:29], v[50:53], v[200:203], v[26:29]
	v_mfma_f32_16x16x32_bf16 v[14:17], v[42:45], v[214:217], v[14:17]
	v_mfma_f32_16x16x32_bf16 v[10:13], v[50:53], v[214:217], v[10:13]
	v_mfma_f32_16x16x32_bf16 v[78:81], v[46:49], v[188:191], v[78:81]
	v_mfma_f32_16x16x32_bf16 v[74:77], v[54:57], v[188:191], v[74:77]
	v_mfma_f32_16x16x32_bf16 v[62:65], v[46:49], v[196:199], v[62:65]
	v_mfma_f32_16x16x32_bf16 v[58:61], v[54:57], v[196:199], v[58:61]
	v_mfma_f32_16x16x32_bf16 v[30:33], v[46:49], v[210:213], v[30:33]
	v_mfma_f32_16x16x32_bf16 v[26:29], v[54:57], v[210:213], v[26:29]
	v_mfma_f32_16x16x32_bf16 v[14:17], v[46:49], v[218:221], v[14:17]
	v_mfma_f32_16x16x32_bf16 v[10:13], v[54:57], v[218:221], v[10:13]
	v_mfma_f32_16x16x32_bf16 v[38:41], v[154:157], v[192:195], v[38:41]
	v_mfma_f32_16x16x32_bf16 v[34:37], v[172:175], v[192:195], v[34:37]
	v_mfma_f32_16x16x32_bf16 v[22:25], v[154:157], v[200:203], v[22:25]
	v_mfma_f32_16x16x32_bf16 v[18:21], v[172:175], v[200:203], v[18:21]
	v_mfma_f32_16x16x32_bf16 v[6:9], v[154:157], v[214:217], v[6:9]
	v_mfma_f32_16x16x32_bf16 v[2:5], v[172:175], v[214:217], v[2:5]
	v_mfma_f32_16x16x32_bf16 v[42:45], v[154:157], v[184:187], v[70:73]
	v_mfma_f32_16x16x32_bf16 v[46:49], v[172:175], v[184:187], v[66:69]
	v_mfma_f32_16x16x32_bf16 v[38:41], v[168:171], v[196:199], v[38:41]
	v_mfma_f32_16x16x32_bf16 v[34:37], v[180:183], v[196:199], v[34:37]
	v_mfma_f32_16x16x32_bf16 v[22:25], v[168:171], v[210:213], v[22:25]
	v_mfma_f32_16x16x32_bf16 v[18:21], v[180:183], v[210:213], v[18:21]
	v_mfma_f32_16x16x32_bf16 v[6:9], v[168:171], v[218:221], v[6:9]
	v_mfma_f32_16x16x32_bf16 v[2:5], v[180:183], v[218:221], v[2:5]
	v_mfma_f32_16x16x32_bf16 v[42:45], v[168:171], v[188:191], v[42:45]
	v_mfma_f32_16x16x32_bf16 v[46:49], v[180:183], v[188:191], v[46:49]
	s_barrier
	s_add_i32 s50, 0, 0x18000
	s_add_i32 s51, 0, 0x1c000
	ds_read_b128 v[50:53], v238
	ds_read_b128 v[54:57], v238 offset:1024
	ds_read_b128 v[66:69], v238 offset:2048
	ds_read_b128 v[70:73], v238 offset:3072
	ds_read_b128 v[154:157], v239
	ds_read_b128 v[168:171], v239 offset:1024
	ds_read_b128 v[172:175], v239 offset:2048
	ds_read_b128 v[180:183], v239 offset:3072
	s_add_u32 s22, s48, 0x160000
	s_addc_u32 s23, s49, 0
	s_mov_b32 m0, s52
	ds_read_b128 v[184:187], v178 offset:32768
	ds_read_b128 v[188:191], v178 offset:33792
	ds_read_b128 v[192:195], v178 offset:34816
	ds_read_b128 v[196:199], v178 offset:35840
	ds_read_b128 v[200:203], v178 offset:36864
	ds_read_b128 v[210:213], v178 offset:37888
	ds_read_b128 v[214:217], v178 offset:38912
	ds_read_b128 v[218:221], v178 offset:39936
	global_load_lds_dwordx4 v162, s[22:23]
	s_mov_b32 m0, s53
	s_nop 0
	global_load_lds_dwordx4 v160, s[22:23]
	s_waitcnt vmcnt(8) lgkmcnt(0)
	s_barrier
	v_mfma_f32_16x16x32_bf16 v[142:145], v[50:53], v[184:187], v[142:145]
	v_mfma_f32_16x16x32_bf16 v[138:141], v[66:69], v[184:187], v[138:141]
	v_mfma_f32_16x16x32_bf16 v[126:129], v[50:53], v[192:195], v[126:129]
	v_mfma_f32_16x16x32_bf16 v[122:125], v[66:69], v[192:195], v[122:125]
	v_mfma_f32_16x16x32_bf16 v[110:113], v[50:53], v[200:203], v[110:113]
	v_mfma_f32_16x16x32_bf16 v[106:109], v[66:69], v[200:203], v[106:109]
	v_mfma_f32_16x16x32_bf16 v[94:97], v[50:53], v[214:217], v[94:97]
	v_mfma_f32_16x16x32_bf16 v[90:93], v[66:69], v[214:217], v[90:93]
	v_mfma_f32_16x16x32_bf16 v[142:145], v[54:57], v[188:191], v[142:145]
	v_mfma_f32_16x16x32_bf16 v[138:141], v[70:73], v[188:191], v[138:141]
	v_mfma_f32_16x16x32_bf16 v[126:129], v[54:57], v[196:199], v[126:129]
	v_mfma_f32_16x16x32_bf16 v[122:125], v[70:73], v[196:199], v[122:125]
	v_mfma_f32_16x16x32_bf16 v[110:113], v[54:57], v[210:213], v[110:113]
	v_mfma_f32_16x16x32_bf16 v[106:109], v[70:73], v[210:213], v[106:109]
	v_mfma_f32_16x16x32_bf16 v[94:97], v[54:57], v[218:221], v[94:97]
	v_mfma_f32_16x16x32_bf16 v[90:93], v[70:73], v[218:221], v[90:93]
	v_mfma_f32_16x16x32_bf16 v[134:137], v[154:157], v[184:187], v[134:137]
	v_mfma_f32_16x16x32_bf16 v[130:133], v[172:175], v[184:187], v[130:133]
	v_mfma_f32_16x16x32_bf16 v[118:121], v[154:157], v[192:195], v[118:121]
	v_mfma_f32_16x16x32_bf16 v[114:117], v[172:175], v[192:195], v[114:117]
	v_mfma_f32_16x16x32_bf16 v[102:105], v[154:157], v[200:203], v[102:105]
	v_mfma_f32_16x16x32_bf16 v[98:101], v[172:175], v[200:203], v[98:101]
	v_mfma_f32_16x16x32_bf16 v[86:89], v[154:157], v[214:217], v[86:89]
	v_mfma_f32_16x16x32_bf16 v[82:85], v[172:175], v[214:217], v[82:85]
	v_mfma_f32_16x16x32_bf16 v[134:137], v[168:171], v[188:191], v[134:137]
	v_mfma_f32_16x16x32_bf16 v[130:133], v[180:183], v[188:191], v[130:133]
	v_mfma_f32_16x16x32_bf16 v[118:121], v[168:171], v[196:199], v[118:121]
	v_mfma_f32_16x16x32_bf16 v[114:117], v[180:183], v[196:199], v[114:117]
	v_mfma_f32_16x16x32_bf16 v[102:105], v[168:171], v[210:213], v[102:105]
	v_mfma_f32_16x16x32_bf16 v[98:101], v[180:183], v[210:213], v[98:101]
	v_mfma_f32_16x16x32_bf16 v[86:89], v[168:171], v[218:221], v[86:89]
	v_mfma_f32_16x16x32_bf16 v[82:85], v[180:183], v[218:221], v[82:85]
	s_barrier
	s_add_i32 s22, s50, s16
	s_mov_b32 m0, s22
	ds_read_b128 v[184:187], v178 offset:49152
	ds_read_b128 v[188:191], v178 offset:50176
	ds_read_b128 v[192:195], v178 offset:51200
	ds_read_b128 v[196:199], v178 offset:52224
	ds_read_b128 v[200:203], v178 offset:53248
	ds_read_b128 v[210:213], v178 offset:54272
	ds_read_b128 v[214:217], v178 offset:55296
	ds_read_b128 v[218:221], v178 offset:56320
	global_load_lds_dwordx4 v0, s[98:99]
	s_add_i32 m0, s22, 0x2000
	s_add_u32 s22, s46, 0x160080
	s_addc_u32 s23, s47, 0
	s_add_i32 s46, s51, s16
	global_load_lds_dwordx4 v158, s[98:99]
	s_mov_b32 m0, s46
	s_nop 0
	global_load_lds_dwordx4 v0, s[22:23]
	s_add_i32 m0, s46, 0x2000
	s_nop 0
	global_load_lds_dwordx4 v158, s[22:23]
	s_mov_b32 m0, s55
	s_nop 0
	global_load_lds_dwordx4 v162, s[100:101]
	s_mov_b32 m0, s56
	s_nop 0
	global_load_lds_dwordx4 v160, s[100:101]
	s_waitcnt vmcnt(8) lgkmcnt(0)
	s_barrier
	v_mfma_f32_16x16x32_bf16 v[78:81], v[50:53], v[184:187], v[78:81]
	v_mfma_f32_16x16x32_bf16 v[74:77], v[66:69], v[184:187], v[74:77]
	v_mfma_f32_16x16x32_bf16 v[62:65], v[50:53], v[192:195], v[62:65]
	v_mfma_f32_16x16x32_bf16 v[58:61], v[66:69], v[192:195], v[58:61]
	v_mfma_f32_16x16x32_bf16 v[30:33], v[50:53], v[200:203], v[30:33]
	v_mfma_f32_16x16x32_bf16 v[26:29], v[66:69], v[200:203], v[26:29]
	v_mfma_f32_16x16x32_bf16 v[14:17], v[50:53], v[214:217], v[14:17]
	v_mfma_f32_16x16x32_bf16 v[10:13], v[66:69], v[214:217], v[10:13]
	v_mfma_f32_16x16x32_bf16 v[78:81], v[54:57], v[188:191], v[78:81]
	v_mfma_f32_16x16x32_bf16 v[74:77], v[70:73], v[188:191], v[74:77]
	v_mfma_f32_16x16x32_bf16 v[62:65], v[54:57], v[196:199], v[62:65]
	v_mfma_f32_16x16x32_bf16 v[58:61], v[70:73], v[196:199], v[58:61]
	v_mfma_f32_16x16x32_bf16 v[30:33], v[54:57], v[210:213], v[30:33]
	v_mfma_f32_16x16x32_bf16 v[26:29], v[70:73], v[210:213], v[26:29]
	v_mfma_f32_16x16x32_bf16 v[14:17], v[54:57], v[218:221], v[14:17]
	v_mfma_f32_16x16x32_bf16 v[10:13], v[70:73], v[218:221], v[10:13]
	v_mfma_f32_16x16x32_bf16 v[42:45], v[154:157], v[184:187], v[42:45]
	v_mfma_f32_16x16x32_bf16 v[70:73], v[168:171], v[188:191], v[42:45]
	v_mfma_f32_16x16x32_bf16 v[42:45], v[172:175], v[184:187], v[46:49]
	v_mfma_f32_16x16x32_bf16 v[38:41], v[154:157], v[192:195], v[38:41]
	v_mfma_f32_16x16x32_bf16 v[34:37], v[172:175], v[192:195], v[34:37]
	v_mfma_f32_16x16x32_bf16 v[22:25], v[154:157], v[200:203], v[22:25]
	v_mfma_f32_16x16x32_bf16 v[18:21], v[172:175], v[200:203], v[18:21]
	v_mfma_f32_16x16x32_bf16 v[6:9], v[154:157], v[214:217], v[6:9]
	v_mfma_f32_16x16x32_bf16 v[2:5], v[172:175], v[214:217], v[2:5]
	v_mfma_f32_16x16x32_bf16 v[66:69], v[180:183], v[188:191], v[42:45]
	v_mfma_f32_16x16x32_bf16 v[38:41], v[168:171], v[196:199], v[38:41]
	v_mfma_f32_16x16x32_bf16 v[34:37], v[180:183], v[196:199], v[34:37]
	v_mfma_f32_16x16x32_bf16 v[22:25], v[168:171], v[210:213], v[22:25]
	v_mfma_f32_16x16x32_bf16 v[18:21], v[180:183], v[210:213], v[18:21]
	v_mfma_f32_16x16x32_bf16 v[6:9], v[168:171], v[218:221], v[6:9]
	v_mfma_f32_16x16x32_bf16 v[2:5], v[180:183], v[218:221], v[2:5]
	s_add_i32 s25, s25, 2
	s_add_u32 s18, s18, 0x100
	s_addc_u32 s19, s19, 0
	s_cmpk_gt_u32 s25, 0x55
	s_mov_b64 s[22:23], s[42:43]
	s_barrier
	s_cbranch_scc0 .LBB0_728
	s_setprio 0
	s_and_b64 vcc, exec, s[12:13]
	s_cbranch_vccz .LBB0_731
	s_barrier
